# P1 v-section epilogue staged through LDS: coalesced f32 rows and transposed bf16 V image stores
# speedup vs baseline: 1.1514x; 1.0072x over previous
; __device__ __forceinline__ unsigned pk2(float lo, float hi) { f32v2_t v = {lo, hi}; bf16v2_t r = __builtin_convertvector(v, bf16v2_t); return __builtin_bit_cast(unsigned, r); }
; __device__ __forceinline__ int accrow(int reg, int hh) { return (reg & 3) + 8 * (reg >> 2) + 4 * hh; }
; __device__ __forceinline__ void vt_store(bf16_t* vt_row, int key32, const f32x16& a, int hh) {
; #pragma unroll
;   for (int g = 0; g < 4; ++g) {
;     const int pos = key32 + (g >> 1) * 16 + hh * 8 + (g & 1) * 4;
;     u32x2 w; w.x = pk2(a[4 * g], a[4 * g + 1]); w.y = pk2(a[4 * g + 2], a[4 * g + 3]);
;     *(u32x2*)(vt_row + pos) = w;
;   }
; }
; __device__ void phase_inproj(const Params& p, char* lds) {
;     ...
; #pragma unroll
;       for (int i = 0; i < 2; ++i)
; #pragma unroll
;         for (int j = 0; j < 2; ++j) {
;           const int mb = m0 + wr * 64 + i * 32; const int nn = n0 - 2048 + wc * 64 + j * 32 + l31;
;           float* o = (samp ? p.out + O_VS + (size_t)(mb - TP) * 1024 : p.out + O_VP + (size_t)mb * 1024) + nn;
; #pragma unroll
;           for (int r = 0; r < 16; ++r) o[(size_t)accrow(r, hh) * 1024] = acc[i][j][r];
;           bf16_t* vt; int key32;
;           if (!samp) { const int b = mb >> 12; vt = (bf16_t*)(ws + W_D2) + ((size_t)(b * 1024 + nn)) * SEQP; key32 = mb & 4095; }
;           else { const int ts = mb - TP; const int b = ts >> 6; vt = (bf16_t*)(ws + W_D2 + SZ_VTP) + ((size_t)(b * 1024 + nn)) * LKS; key32 = PAST + (ts & 63); }
;           vt_store(vt, key32, acc[i][j], hh);
;         }
.LBB0_268:
	v_and_b32_e32 v165, 63, v181
	v_lshrrev_b32_e32 v164, 6, v181
	v_and_b32_e32 v109, 31, v165
	v_lshrrev_b32_e32 v111, 5, v165
	v_mul_u32_u24_e32 v111, 0x440, v111
	v_mul_u32_u24_e32 v167, 0x2200, v164
	v_lshl_add_u32 v138, v109, 2, v111
	v_add_u32_e32 v138, v138, v167
	v_add_u32_e32 v138, 0x8000, v138
	v_add_u32_e32 v139, 0x8000, v167
	v_lshrrev_b32_e32 v140, 4, v165
	v_and_b32_e32 v141, 15, v165
	v_and_b32_e32 v170, 3, v165
	v_lshrrev_b32_e32 v171, 2, v165
	v_and_b32_e32 v109, 1, v170
	v_lshrrev_b32_e32 v111, 1, v170
	v_mul_u32_u24_e32 v109, 0x440, v109
	v_mul_u32_u24_e32 v111, 0x1100, v111
	v_add3_u32 v168, v139, v109, v111
	v_lshl_add_u32 v168, v171, 2, v168
	v_mul_u32_u24_e32 v109, 0x110, v140
	v_add_u32_e32 v139, v139, v109
	v_lshl_add_u32 v139, v141, 4, v139
	v_readlane_b32 s2, v248, 4
	v_readlane_b32 s3, v248, 5
	s_sub_i32 s35, s54, 0x800
	s_cmpk_gt_i32 s52, 0xff
	s_cbranch_scc1 .Lp1v_samp
	s_lshl_b32 s0, s53, 12
	s_add_i32 s0, s0, 0x10200000
	s_lshr_b32 s1, s53, 12
	s_lshl_b32 s1, s1, 10
	s_add_i32 s1, s1, s35
	s_mul_i32 s1, s1, 0x2080
	s_and_b32 s34, s53, 0xfff
	s_lshl_b32 s34, s34, 1
	s_add_i32 s1, s1, s34
	s_add_i32 s1, s1, 0x1079e000
	s_movk_i32 s34, 0x2080
	v_and_b32_e32 v109, 1, v164
	v_lshl_add_u32 v109, v109, 6, v171
	v_lshrrev_b32_e32 v111, 1, v164
	v_lshlrev_b32_e32 v111, 7, v111
	s_branch .Lp1v_go
.Lp1v_samp:
	s_sub_i32 s34, s53, 0x8000
	s_lshl_b32 s0, s34, 12
	s_add_i32 s0, s0, 0x19800000
	s_lshr_b32 s1, s34, 6
	s_lshl_b32 s1, s1, 10
	s_add_i32 s1, s1, s35
	s_mul_i32 s1, s1, 0x1080
	s_add_i32 s1, s1, 0x1000
	s_add_i32 s1, s1, 0x1489e000
	s_movk_i32 s34, 0x1080
	v_and_b32_e32 v109, 1, v164
	v_lshl_add_u32 v109, v109, 6, v171
	v_lshrrev_b32_e32 v111, 1, v164
	v_lshl_add_u32 v109, v111, 10, v109
	v_mov_b32_e32 v111, 0
.Lp1v_go:
	s_lshl_b32 s35, s35, 2
	s_add_i32 s0, s0, s35
	v_mul_lo_u32 v169, v109, s34
	v_lshl_add_u32 v111, v170, 4, v111
	v_add3_u32 v169, v169, v111, s1
	s_lshl_b32 s35, s34, 4
	v_lshrrev_b32_e32 v166, 1, v164
	v_mul_u32_u24_e32 v166, 0x40000, v166
	v_mul_u32_u24_e32 v167, 0x1000, v140
	v_add_u32_e32 v166, v166, v167
	v_and_b32_e32 v167, 1, v164
	v_mul_u32_u24_e32 v167, 0x100, v167
	v_lshl_add_u32 v167, v141, 4, v167
	v_add3_u32 v166, v166, v167, s0
	ds_write_b32 v138, v48 offset:0
	ds_write_b32 v138, v49 offset:272
	ds_write_b32 v138, v50 offset:544
	ds_write_b32 v138, v51 offset:816
	ds_write_b32 v138, v52 offset:2176
	ds_write_b32 v138, v53 offset:2448
	ds_write_b32 v138, v54 offset:2720
	ds_write_b32 v138, v55 offset:2992
	ds_write_b32 v138, v56 offset:4352
	ds_write_b32 v138, v57 offset:4624
	ds_write_b32 v138, v58 offset:4896
	ds_write_b32 v138, v59 offset:5168
	ds_write_b32 v138, v60 offset:6528
	ds_write_b32 v138, v61 offset:6800
	ds_write_b32 v138, v62 offset:7072
	ds_write_b32 v138, v63 offset:7344
	ds_write_b32 v138, v32 offset:128
	ds_write_b32 v138, v33 offset:400
	ds_write_b32 v138, v34 offset:672
	ds_write_b32 v138, v35 offset:944
	ds_write_b32 v138, v36 offset:2304
	ds_write_b32 v138, v37 offset:2576
	ds_write_b32 v138, v38 offset:2848
	ds_write_b32 v138, v39 offset:3120
	ds_write_b32 v138, v40 offset:4480
	ds_write_b32 v138, v41 offset:4752
	ds_write_b32 v138, v42 offset:5024
	ds_write_b32 v138, v43 offset:5296
	ds_write_b32 v138, v44 offset:6656
	ds_write_b32 v138, v45 offset:6928
	ds_write_b32 v138, v46 offset:7200
	ds_write_b32 v138, v47 offset:7472
	s_waitcnt lgkmcnt(0)
	ds_read_b128 v[32:35], v139 offset:0
	ds_read_b128 v[36:39], v139 offset:1088
	ds_read_b128 v[40:43], v139 offset:2176
	ds_read_b128 v[44:47], v139 offset:3264
	ds_read_b128 v[48:51], v139 offset:4352
	ds_read_b128 v[52:55], v139 offset:5440
	ds_read_b128 v[56:59], v139 offset:6528
	ds_read_b128 v[60:63], v139 offset:7616
	s_waitcnt lgkmcnt(7)
	global_store_dwordx4 v166, v[32:35], s[2:3] nt
	v_add_u32_e32 v166, 0x4000, v166
	s_waitcnt lgkmcnt(6)
	global_store_dwordx4 v166, v[36:39], s[2:3] nt
	v_add_u32_e32 v166, 0x4000, v166
	s_waitcnt lgkmcnt(5)
	global_store_dwordx4 v166, v[40:43], s[2:3] nt
	v_add_u32_e32 v166, 0x4000, v166
	s_waitcnt lgkmcnt(4)
	global_store_dwordx4 v166, v[44:47], s[2:3] nt
	v_add_u32_e32 v166, 0x4000, v166
	s_waitcnt lgkmcnt(3)
	global_store_dwordx4 v166, v[48:51], s[2:3] nt
	v_add_u32_e32 v166, 0x4000, v166
	s_waitcnt lgkmcnt(2)
	global_store_dwordx4 v166, v[52:55], s[2:3] nt
	v_add_u32_e32 v166, 0x4000, v166
	s_waitcnt lgkmcnt(1)
	global_store_dwordx4 v166, v[56:59], s[2:3] nt
	v_add_u32_e32 v166, 0x4000, v166
	s_waitcnt lgkmcnt(0)
	global_store_dwordx4 v166, v[60:63], s[2:3] nt
	v_add_u32_e32 v166, 0x4000, v166
	ds_read_b32 v32, v168 offset:0
	ds_read_b32 v33, v168 offset:272
	ds_read_b32 v34, v168 offset:544
	ds_read_b32 v35, v168 offset:816
	ds_read_b32 v36, v168 offset:2176
	ds_read_b32 v37, v168 offset:2448
	ds_read_b32 v38, v168 offset:2720
	ds_read_b32 v39, v168 offset:2992
	s_waitcnt lgkmcnt(0)
	v_cvt_pk_bf16_f32 v32, v32, v33
	v_cvt_pk_bf16_f32 v33, v34, v35
	v_cvt_pk_bf16_f32 v34, v36, v37
	v_cvt_pk_bf16_f32 v35, v38, v39
	global_store_dwordx4 v169, v[32:35], s[96:97]
	v_add_u32_e32 v169, s35, v169
	ds_read_b32 v40, v168 offset:64
	ds_read_b32 v41, v168 offset:336
	ds_read_b32 v42, v168 offset:608
	ds_read_b32 v43, v168 offset:880
	ds_read_b32 v44, v168 offset:2240
	ds_read_b32 v45, v168 offset:2512
	ds_read_b32 v46, v168 offset:2784
	ds_read_b32 v47, v168 offset:3056
	s_waitcnt lgkmcnt(0)
; __device__ __forceinline__ unsigned pk2(float lo, float hi) { f32v2_t v = {lo, hi}; bf16v2_t r = __builtin_convertvector(v, bf16v2_t); return __builtin_bit_cast(unsigned, r); }
; __device__ __forceinline__ int accrow(int reg, int hh) { return (reg & 3) + 8 * (reg >> 2) + 4 * hh; }
; __device__ __forceinline__ void vt_store(bf16_t* vt_row, int key32, const f32x16& a, int hh) {
; #pragma unroll
;   for (int g = 0; g < 4; ++g) {
;     const int pos = key32 + (g >> 1) * 16 + hh * 8 + (g & 1) * 4;
;     u32x2 w; w.x = pk2(a[4 * g], a[4 * g + 1]); w.y = pk2(a[4 * g + 2], a[4 * g + 3]);
;     *(u32x2*)(vt_row + pos) = w;
;   }
; }
; __device__ void phase_inproj(const Params& p, char* lds) {
;     ...
; #pragma unroll
;       for (int i = 0; i < 2; ++i)
; #pragma unroll
;         for (int j = 0; j < 2; ++j) {
;           const int mb = m0 + wr * 64 + i * 32; const int nn = n0 - 2048 + wc * 64 + j * 32 + l31;
;           float* o = (samp ? p.out + O_VS + (size_t)(mb - TP) * 1024 : p.out + O_VP + (size_t)mb * 1024) + nn;
; #pragma unroll
;           for (int r = 0; r < 16; ++r) o[(size_t)accrow(r, hh) * 1024] = acc[i][j][r];
;           bf16_t* vt; int key32;
;           if (!samp) { const int b = mb >> 12; vt = (bf16_t*)(ws + W_D2) + ((size_t)(b * 1024 + nn)) * SEQP; key32 = mb & 4095; }
;           else { const int ts = mb - TP; const int b = ts >> 6; vt = (bf16_t*)(ws + W_D2 + SZ_VTP) + ((size_t)(b * 1024 + nn)) * LKS; key32 = PAST + (ts & 63); }
;           vt_store(vt, key32, acc[i][j], hh);
;         }
	v_cvt_pk_bf16_f32 v40, v40, v41
	v_cvt_pk_bf16_f32 v41, v42, v43
	v_cvt_pk_bf16_f32 v42, v44, v45
	v_cvt_pk_bf16_f32 v43, v46, v47
	global_store_dwordx4 v169, v[40:43], s[96:97]
	v_add_u32_e32 v169, s35, v169
	ds_read_b32 v48, v168 offset:128
	ds_read_b32 v49, v168 offset:400
	ds_read_b32 v50, v168 offset:672
	ds_read_b32 v51, v168 offset:944
	ds_read_b32 v52, v168 offset:2304
	ds_read_b32 v53, v168 offset:2576
	ds_read_b32 v54, v168 offset:2848
	ds_read_b32 v55, v168 offset:3120
	s_waitcnt lgkmcnt(0)
	v_cvt_pk_bf16_f32 v48, v48, v49
	v_cvt_pk_bf16_f32 v49, v50, v51
	v_cvt_pk_bf16_f32 v50, v52, v53
	v_cvt_pk_bf16_f32 v51, v54, v55
	global_store_dwordx4 v169, v[48:51], s[96:97]
	v_add_u32_e32 v169, s35, v169
	ds_read_b32 v56, v168 offset:192
	ds_read_b32 v57, v168 offset:464
	ds_read_b32 v58, v168 offset:736
	ds_read_b32 v59, v168 offset:1008
	ds_read_b32 v60, v168 offset:2368
	ds_read_b32 v61, v168 offset:2640
	ds_read_b32 v62, v168 offset:2912
	ds_read_b32 v63, v168 offset:3184
	s_waitcnt lgkmcnt(0)
	v_cvt_pk_bf16_f32 v56, v56, v57
	v_cvt_pk_bf16_f32 v57, v58, v59
	v_cvt_pk_bf16_f32 v58, v60, v61
	v_cvt_pk_bf16_f32 v59, v62, v63
	global_store_dwordx4 v169, v[56:59], s[96:97]
	v_add_u32_e32 v169, s35, v169
	s_lshl_b32 s1, s35, 2
	s_sub_i32 s1, 64, s1
	v_add_u32_e32 v169, s1, v169
	ds_write_b32 v138, v16 offset:0
	ds_write_b32 v138, v17 offset:272
	ds_write_b32 v138, v18 offset:544
	ds_write_b32 v138, v19 offset:816
	ds_write_b32 v138, v20 offset:2176
	ds_write_b32 v138, v21 offset:2448
	ds_write_b32 v138, v22 offset:2720
	ds_write_b32 v138, v23 offset:2992
	ds_write_b32 v138, v24 offset:4352
	ds_write_b32 v138, v25 offset:4624
	ds_write_b32 v138, v26 offset:4896
	ds_write_b32 v138, v27 offset:5168
	ds_write_b32 v138, v28 offset:6528
	ds_write_b32 v138, v29 offset:6800
	ds_write_b32 v138, v30 offset:7072
	ds_write_b32 v138, v31 offset:7344
	ds_write_b32 v138, v0 offset:128
	ds_write_b32 v138, v1 offset:400
	ds_write_b32 v138, v2 offset:672
	ds_write_b32 v138, v3 offset:944
	ds_write_b32 v138, v4 offset:2304
	ds_write_b32 v138, v5 offset:2576
	ds_write_b32 v138, v6 offset:2848
	ds_write_b32 v138, v7 offset:3120
	ds_write_b32 v138, v8 offset:4480
	ds_write_b32 v138, v9 offset:4752
	ds_write_b32 v138, v10 offset:5024
	ds_write_b32 v138, v11 offset:5296
	ds_write_b32 v138, v12 offset:6656
	ds_write_b32 v138, v13 offset:6928
	ds_write_b32 v138, v14 offset:7200
	ds_write_b32 v138, v15 offset:7472
	s_waitcnt lgkmcnt(0)
	ds_read_b128 v[0:3], v139 offset:0
	ds_read_b128 v[4:7], v139 offset:1088
	ds_read_b128 v[8:11], v139 offset:2176
	ds_read_b128 v[12:15], v139 offset:3264
	ds_read_b128 v[16:19], v139 offset:4352
	ds_read_b128 v[20:23], v139 offset:5440
	ds_read_b128 v[24:27], v139 offset:6528
	ds_read_b128 v[28:31], v139 offset:7616
	s_waitcnt lgkmcnt(7)
	global_store_dwordx4 v166, v[0:3], s[2:3] nt
	v_add_u32_e32 v166, 0x4000, v166
	s_waitcnt lgkmcnt(6)
	global_store_dwordx4 v166, v[4:7], s[2:3] nt
	v_add_u32_e32 v166, 0x4000, v166
	s_waitcnt lgkmcnt(5)
	global_store_dwordx4 v166, v[8:11], s[2:3] nt
	v_add_u32_e32 v166, 0x4000, v166
	s_waitcnt lgkmcnt(4)
	global_store_dwordx4 v166, v[12:15], s[2:3] nt
	v_add_u32_e32 v166, 0x4000, v166
	s_waitcnt lgkmcnt(3)
	global_store_dwordx4 v166, v[16:19], s[2:3] nt
	v_add_u32_e32 v166, 0x4000, v166
	s_waitcnt lgkmcnt(2)
	global_store_dwordx4 v166, v[20:23], s[2:3] nt
	v_add_u32_e32 v166, 0x4000, v166
	s_waitcnt lgkmcnt(1)
	global_store_dwordx4 v166, v[24:27], s[2:3] nt
	v_add_u32_e32 v166, 0x4000, v166
	s_waitcnt lgkmcnt(0)
	global_store_dwordx4 v166, v[28:31], s[2:3] nt
	v_add_u32_e32 v166, 0x4000, v166
	ds_read_b32 v0, v168 offset:0
	ds_read_b32 v1, v168 offset:272
	ds_read_b32 v2, v168 offset:544
	ds_read_b32 v3, v168 offset:816
	ds_read_b32 v4, v168 offset:2176
	ds_read_b32 v5, v168 offset:2448
	ds_read_b32 v6, v168 offset:2720
	ds_read_b32 v7, v168 offset:2992
	s_waitcnt lgkmcnt(0)
	v_cvt_pk_bf16_f32 v0, v0, v1
	v_cvt_pk_bf16_f32 v1, v2, v3
	v_cvt_pk_bf16_f32 v2, v4, v5
	v_cvt_pk_bf16_f32 v3, v6, v7
	global_store_dwordx4 v169, v[0:3], s[96:97]
	v_add_u32_e32 v169, s35, v169
	ds_read_b32 v8, v168 offset:64
	ds_read_b32 v9, v168 offset:336
	ds_read_b32 v10, v168 offset:608
	ds_read_b32 v11, v168 offset:880
	ds_read_b32 v12, v168 offset:2240
	ds_read_b32 v13, v168 offset:2512
	ds_read_b32 v14, v168 offset:2784
	ds_read_b32 v15, v168 offset:3056
	s_waitcnt lgkmcnt(0)
	v_cvt_pk_bf16_f32 v8, v8, v9
	v_cvt_pk_bf16_f32 v9, v10, v11
	v_cvt_pk_bf16_f32 v10, v12, v13
	v_cvt_pk_bf16_f32 v11, v14, v15
	global_store_dwordx4 v169, v[8:11], s[96:97]
	v_add_u32_e32 v169, s35, v169
	ds_read_b32 v16, v168 offset:128
	ds_read_b32 v17, v168 offset:400
	ds_read_b32 v18, v168 offset:672
	ds_read_b32 v19, v168 offset:944
	ds_read_b32 v20, v168 offset:2304
	ds_read_b32 v21, v168 offset:2576
	ds_read_b32 v22, v168 offset:2848
	ds_read_b32 v23, v168 offset:3120
	s_waitcnt lgkmcnt(0)
	v_cvt_pk_bf16_f32 v16, v16, v17
	v_cvt_pk_bf16_f32 v17, v18, v19
	v_cvt_pk_bf16_f32 v18, v20, v21
	v_cvt_pk_bf16_f32 v19, v22, v23
	global_store_dwordx4 v169, v[16:19], s[96:97]
	v_add_u32_e32 v169, s35, v169
	ds_read_b32 v24, v168 offset:192
	ds_read_b32 v25, v168 offset:464
	ds_read_b32 v26, v168 offset:736
	ds_read_b32 v27, v168 offset:1008
	ds_read_b32 v28, v168 offset:2368
	ds_read_b32 v29, v168 offset:2640
	ds_read_b32 v30, v168 offset:2912
	ds_read_b32 v31, v168 offset:3184
	s_waitcnt lgkmcnt(0)
	v_cvt_pk_bf16_f32 v24, v24, v25
	v_cvt_pk_bf16_f32 v25, v26, v27
	v_cvt_pk_bf16_f32 v26, v28, v29
	v_cvt_pk_bf16_f32 v27, v30, v31
	global_store_dwordx4 v169, v[24:27], s[96:97]
	v_add_u32_e32 v169, s35, v169
	s_mov_b32 s34, 4
